# k20: k19 + attention unit prologue issues the second K staging piece with the first load burst (one fewer memory round trip per unit)
# speedup vs baseline: 1.0135x; 1.0063x over previous
; #define AT_LOAD(t_, S) do { const int tc_ = (t_) < NT ? (t_) : NT - 1; const size_t off_ = (size_t)tc_ * 64; k0r##S = *(const u32x4*)(kg0 + off_ * 768); k1r##S = *(const u32x4*)(kg1 + off_ * 768); vr##S = *(const u32x4*)(vg + off_ * 512); } while (0)
; #define AT_STORE(bo_, S) do { unsigned char* lb_ = lds + (bo_); *(u32x4*)(lb_ + ks0) = k0r##S; if (tid < 256) *(u32x4*)(lb_ + ks1) = k1r##S; *(u32x4*)(lb_ + vs0) = vr##S; } while (0)
; __device__ __forceinline__ void attn_unit(const Ctx& c, int bh, int qb, const bf16_t* Q, const bf16_t* Kb, const bf16_t* Vb, bf16_t* O) {
;     ...
;     { const bf16_t* qp = Q + (rowbase + q0 + wid * 32 + r32) * 768 + h * 96 + hi * 8;
; #pragma unroll
;       for (int d0 = 0; d0 < 6; ++d0) qr[d0] = *(const bf16x8*)(qp + d0 * 16); }
;     const int NT = 4 * qb + 4, ntw = 4 * qb + (wid >> 1) + 1;
;     const int kr0 = tid / 12, kc0 = tid % 12, kr1 = (512 + tid) / 12, kc1 = (512 + tid) % 12;
;     const bf16_t* kg0 = Kb + (rowbase + kr0) * 768 + h * 96 + kc0 * 8;
;     const bf16_t* kg1 = Kb + (rowbase + kr1) * 768 + h * 96 + kc1 * 8;
;     const bf16_t* vg = Vb + (rowbase + (tid >> 3)) * 512 + h * 64 + (tid & 7) * 8;
;     const int ks0 = AT_K + kc0 * 1024 + ((kr0 & 48) | ((kr0 ^ kc0) & 15)) * 16, ks1 = AT_K + kc1 * 1024 + ((kr1 & 48) | ((kr1 ^ kc1) & 15)) * 16;
;     const int vs0 = AT_V + (tid >> 3) * AT_VP + (tid & 7) * 16;
;     const int kx = r32 ^ hi;
;     const int vtb = AT_V + (4 * hi + ((lane & 15) >> 2)) * AT_VP + (16 * ((lane >> 4) & 1) + 4 * (lane & 3)) * 2;
;     u32x4 k0rA, k1rA, vrA, k0rB, k1rB, vrB;
;     ...
;     int b0 = 0, b1 = AT_BUF, b2 = 2 * AT_BUF;
;     float mrow = -1e30f, lsum = 0.f;
;     f32x16 o[2]; o[0] = f32x16{}; o[1] = f32x16{};
;     AT_LOAD(0, A); AT_LOAD(1, B); AT_STORE(b0, A); AT_LOAD(2, A); AT_STORE(b1, B); AT_LOAD(3, B);
;     __syncthreads();
.LBB0_285:
	s_lshl_b32 s6, s3, 7
	s_and_b32 s6, s6, 0x7000
	v_readlane_b32 s8, v255, 13
	s_lshl_b32 s7, s5, 8
	s_add_i32 s8, s6, s8
	s_add_i32 s46, s8, s7
	s_bfe_u32 s4, s3, 0x30002
	v_or_b32_e32 v2, s46, v146
	v_mov_b64_e32 v[0:1], s[86:87]
	s_movk_i32 s10, 0x600
	v_mad_u64_u32 v[0:1], s[8:9], v2, s10, v[0:1]
	s_mul_i32 s16, s4, 0xc0
	v_lshl_add_u64 v[0:1], v[0:1], 0, s[16:17]
	v_lshl_add_u64 v[0:1], v[0:1], 0, v[210:211]
	s_mov_b32 s7, s17
	global_load_dwordx4 v[98:101], v[0:1], off
	global_load_dwordx4 v[102:105], v[0:1], off offset:32
	global_load_dwordx4 v[106:109], v[0:1], off offset:64
	global_load_dwordx4 v[110:113], v[0:1], off offset:96
	global_load_dwordx4 v[114:117], v[0:1], off offset:128
	global_load_dwordx4 v[118:121], v[0:1], off offset:160
	v_lshl_add_u64 v[0:1], s[6:7], 0, v[148:149]
	v_mov_b64_e32 v[2:3], s[84:85]
	v_mad_u64_u32 v[4:5], s[8:9], v0, s10, v[2:3]
	v_mad_i32_i24 v5, v1, s10, v5
	v_lshl_add_u64 v[0:1], v[4:5], 0, s[16:17]
	v_lshl_add_u64 v[194:195], v[152:153], 1, v[0:1]
	v_lshl_add_u64 v[0:1], s[6:7], 0, v[150:151]
	v_mad_u64_u32 v[2:3], s[8:9], v0, s10, v[2:3]
	v_mad_i32_i24 v3, v1, s10, v3
	v_lshl_add_u64 v[0:1], v[2:3], 0, s[16:17]
	v_lshl_add_u64 v[196:197], v[154:155], 1, v[0:1]
	v_lshl_add_u64 v[0:1], s[6:7], 0, v[156:157]
	v_lshlrev_b64 v[0:1], 10, v[0:1]
	v_lshl_add_u64 v[0:1], s[80:81], 0, v[0:1]
	s_lshl_b32 s16, s4, 7
	v_lshl_add_u64 v[0:1], v[0:1], 0, s[16:17]
	v_mov_b32_e32 v191, v211
	v_lshl_add_u64 v[198:199], v[0:1], 0, v[190:191]
	v_add_co_u32_e32 v0, vcc, 0x18000, v194
	global_load_dwordx4 v[20:23], v[194:195], off
	global_load_dwordx4 v[12:15], v[198:199], off
	v_addc_co_u32_e32 v1, vcc, 0, v195, vcc
	v_add_co_u32_e32 v2, vcc, 0x18000, v196
	s_movk_i32 s2, 0x600
	s_nop 0
	v_addc_co_u32_e32 v3, vcc, 0, v197, vcc
	global_load_dwordx4 v[8:11], v[0:1], off
	global_load_dwordx4 v[4:7], v[2:3], off
	v_add_co_u32_e32 v0, vcc, 0x10000, v198
	v_add_u32_e32 v18, 0, v97
	s_nop 0
	v_addc_co_u32_e32 v1, vcc, 0, v199, vcc
	global_load_dwordx4 v[0:3], v[0:1], off
	global_load_dwordx4 v[142:145], v[196:197], off
	v_add_u32_e32 v17, 0, v147
	s_waitcnt vmcnt(5)
	ds_write_b128 v18, v[20:23]
	s_and_saveexec_b64 s[6:7], s[42:43]
	s_cbranch_execz .LBB0_287
	s_waitcnt vmcnt(0)
	ds_write_b128 v17, v[142:145]
.LBB0_287:
	s_or_b64 exec, exec, s[6:7]
	v_add_u32_e32 v16, 0, v200
	s_waitcnt vmcnt(4)
	ds_write_b128 v16, v[12:15] offset:12288
	v_add_co_u32_e32 v12, vcc, 0x30000, v194
	s_waitcnt vmcnt(3)
	ds_write_b128 v18, v[8:11] offset:24576
	v_addc_co_u32_e32 v13, vcc, 0, v195, vcc
	global_load_dwordx4 v[122:125], v[12:13], off
	v_add_co_u32_e32 v12, vcc, 0x30000, v196
	s_nop 1
	v_addc_co_u32_e32 v13, vcc, 0, v197, vcc
	global_load_dwordx4 v[126:129], v[12:13], off
	v_add_co_u32_e32 v12, vcc, 0x20000, v198
	s_nop 1
	v_addc_co_u32_e32 v13, vcc, 0, v199, vcc
	global_load_dwordx4 v[130:133], v[12:13], off
	s_and_saveexec_b64 s[6:7], s[42:43]
	s_cbranch_execz .LBB0_289
	s_waitcnt vmcnt(4)
	ds_write_b128 v17, v[4:7] offset:24576
; #define AT_LOAD(t_, S) do { const int tc_ = (t_) < NT ? (t_) : NT - 1; const size_t off_ = (size_t)tc_ * 64; k0r##S = *(const u32x4*)(kg0 + off_ * 768); k1r##S = *(const u32x4*)(kg1 + off_ * 768); vr##S = *(const u32x4*)(vg + off_ * 512); } while (0)
; #define AT_STORE(bo_, S) do { unsigned char* lb_ = lds + (bo_); *(u32x4*)(lb_ + ks0) = k0r##S; if (tid < 256) *(u32x4*)(lb_ + ks1) = k1r##S; *(u32x4*)(lb_ + vs0) = vr##S; } while (0)
; __device__ __forceinline__ void attn_unit(const Ctx& c, int bh, int qb, const bf16_t* Q, const bf16_t* Kb, const bf16_t* Vb, bf16_t* O) {
;     ...
;     AT_LOAD(0, A); AT_LOAD(1, B); AT_STORE(b0, A); AT_LOAD(2, A); AT_STORE(b1, B); AT_LOAD(3, B);
;     __syncthreads();
;     f32x16 pA0, pA1, pB0, pB1;
;     AT_QK(pA0, pA1, b0);
.LBB0_289:
	s_or_b64 exec, exec, s[6:7]
	s_waitcnt vmcnt(4)
	ds_write_b128 v16, v[0:3] offset:36864
	v_add_co_u32_e32 v0, vcc, 0x48000, v194
	s_mov_b32 s56, 0
	s_nop 0
	v_addc_co_u32_e32 v1, vcc, 0, v195, vcc
	global_load_dwordx4 v[134:137], v[0:1], off
	v_add_co_u32_e32 v0, vcc, 0x48000, v196
	s_mov_b32 s57, s56
	s_nop 0
	v_addc_co_u32_e32 v1, vcc, 0, v197, vcc
	global_load_dwordx4 v[138:141], v[0:1], off
	v_add_co_u32_e32 v0, vcc, 0x30000, v198
	s_mov_b32 s58, s56
	s_nop 0
	v_addc_co_u32_e32 v1, vcc, 0, v199, vcc
	global_load_dwordx4 v[142:145], v[0:1], off
	v_add_u32_e32 v0, v203, v204
	s_waitcnt lgkmcnt(0)
	s_barrier
	ds_read_b128 v[16:19], v0 offset:512
	ds_read_b128 v[20:23], v0
	s_waitcnt lgkmcnt(0)
	v_mfma_f32_32x32x16_bf16 v[32:47], v[20:23], v[98:101], 0
	v_add_u32_e32 v20, v203, v205
	s_mov_b32 s59, s56
	s_mov_b32 s60, s56
	s_mov_b32 s61, s56
	s_mov_b32 s62, s56
	s_mov_b32 s63, s56
	s_mov_b32 s64, s56
	v_mfma_f32_32x32x16_bf16 v[48:63], v[16:19], v[98:101], 0
	ds_read_b128 v[16:19], v20 offset:2560
	ds_read_b128 v[20:23], v20 offset:2048
	s_mov_b32 s65, s56
	s_mov_b32 s66, s56
	s_mov_b32 s67, s56
	s_mov_b32 s68, s56
	s_mov_b32 s69, s56
	s_mov_b32 s70, s56
	s_waitcnt lgkmcnt(0)
	v_mfma_f32_32x32x16_bf16 v[32:47], v[20:23], v[102:105], v[32:47]
	v_add_u32_e32 v20, v203, v206
	s_mov_b32 s71, s56
	v_mov_b64_e32 v[0:1], s[56:57]
	v_mov_b64_e32 v[14:15], s[70:71]
	s_lshl_b32 s5, s5, 2
	v_readlane_b32 s6, v254, 63
	v_mov_b64_e32 v[2:3], s[58:59]
	v_mfma_f32_32x32x16_bf16 v[48:63], v[16:19], v[102:105], v[48:63]
	ds_read_b128 v[16:19], v20 offset:4608
	ds_read_b128 v[20:23], v20 offset:4096
	v_mov_b64_e32 v[4:5], s[60:61]
	v_mov_b64_e32 v[6:7], s[62:63]
	v_mov_b64_e32 v[8:9], s[64:65]
	v_mov_b64_e32 v[10:11], s[66:67]
	v_mov_b64_e32 v[12:13], s[68:69]
	s_mov_b32 s47, s17
	s_waitcnt lgkmcnt(0)
	v_mfma_f32_32x32x16_bf16 v[32:47], v[20:23], v[106:109], v[32:47]
	v_add_u32_e32 v20, v203, v207
	s_lshl_b32 s4, s4, 6
	s_add_i32 s8, s5, 4
	s_add_i32 s9, s5, s6
	s_or_b32 s10, s5, 3
	v_mov_b32_e32 v191, 0
	v_mov_b32_e32 v174, 0
	v_mov_b32_e32 v175, 0
	v_mov_b32_e32 v176, 0
	v_mov_b32_e32 v177, 0
	v_mov_b32_e32 v178, 0
	v_mov_b32_e32 v179, 0
	v_mov_b32_e32 v180, 0
	v_mov_b32_e32 v181, 0
	v_mov_b32_e32 v182, 0
	v_mov_b32_e32 v183, 0
	v_mov_b32_e32 v184, 0
	v_mov_b32_e32 v185, 0
	v_mov_b32_e32 v186, 0
	v_mov_b32_e32 v187, 0
	v_mov_b32_e32 v188, 0
	v_mov_b32_e32 v189, 0
	v_mfma_f32_32x32x16_bf16 v[48:63], v[16:19], v[106:109], v[48:63]
	ds_read_b128 v[16:19], v20 offset:6656
	ds_read_b128 v[20:23], v20 offset:6144
	s_mov_b32 s12, 0xc000
	s_movk_i32 s11, 0x6000
	s_mov_b32 s13, s56
	s_waitcnt lgkmcnt(0)
	v_mfma_f32_32x32x16_bf16 v[32:47], v[20:23], v[110:113], v[32:47]
	v_add_u32_e32 v20, v203, v208
	v_mfma_f32_32x32x16_bf16 v[48:63], v[16:19], v[110:113], v[48:63]
	ds_read_b128 v[16:19], v20 offset:8704
	ds_read_b128 v[20:23], v20 offset:8192
	s_waitcnt lgkmcnt(0)
	v_mfma_f32_32x32x16_bf16 v[32:47], v[20:23], v[114:117], v[32:47]
	v_add_u32_e32 v20, v203, v209
	v_mfma_f32_32x32x16_bf16 v[48:63], v[16:19], v[114:117], v[48:63]
	ds_read_b128 v[16:19], v20 offset:10752
	ds_read_b128 v[20:23], v20 offset:10240
	s_waitcnt lgkmcnt(0)
	v_mfma_f32_32x32x16_bf16 v[32:47], v[20:23], v[118:121], v[32:47]
	v_mfma_f32_32x32x16_bf16 v[48:63], v[16:19], v[118:121], v[48:63]
	v_mov_b64_e32 v[30:31], v[14:15]
	v_mov_b64_e32 v[28:29], v[12:13]
	v_mov_b64_e32 v[26:27], v[10:11]
	v_mov_b64_e32 v[24:25], v[8:9]
	v_mov_b64_e32 v[22:23], v[6:7]
	v_mov_b64_e32 v[20:21], v[4:5]
	v_mov_b64_e32 v[18:19], v[2:3]
	v_mov_b64_e32 v[16:17], v[0:1]
	s_nop 15
	v_max3_f32 v232, v32, v33, v34
	v_max3_f32 v233, v35, v36, v37
	v_max3_f32 v232, v232, v38, v39
	v_max3_f32 v233, v233, v40, v41
	v_max3_f32 v232, v232, v42, v43
	v_max3_f32 v233, v233, v44, v45
	v_max3_f32 v232, v232, v46, v47
	v_max3_f32 v233, v233, v48, v49
	v_max3_f32 v232, v232, v50, v51
	v_max3_f32 v233, v233, v52, v53
	v_max3_f32 v232, v232, v54, v55
	v_max3_f32 v233, v233, v56, v57
	v_max3_f32 v232, v232, v58, v59
	v_max3_f32 v233, v233, v60, v61
	v_max3_f32 v232, v232, v62, v63
	v_max3_f32 v232, v232, v233, v233
